# plus phase-5 copy loops unrolled (shift-state row copy 14 loads in flight, conv-state copy 8 in flight)
# speedup vs baseline: 1.0046x; 1.0046x over previous
.LBB0_667:
	s_mov_b32 s88, 0x1000
	s_mov_b32 s89, 0
	v_lshl_add_u64 v[196:197], v[18:19], 0, s[88:89]
	v_lshl_add_u64 v[202:203], v[16:17], 0, s[88:89]
	v_lshl_add_u64 v[198:199], v[196:197], 0, s[88:89]
	v_lshl_add_u64 v[204:205], v[202:203], 0, s[88:89]
	v_lshl_add_u64 v[200:201], v[198:199], 0, s[88:89]
	v_lshl_add_u64 v[206:207], v[204:205], 0, s[88:89]
	v_cmp_gt_u32_e64 s[90:91], 8, v136
	global_load_dwordx4 v[140:143], v[18:19], off offset:0
	global_load_dwordx4 v[144:147], v[18:19], off offset:1024
	global_load_dwordx4 v[148:151], v[18:19], off offset:2048
	global_load_dwordx4 v[152:155], v[18:19], off offset:3072
	global_load_dwordx4 v[156:159], v[196:197], off offset:0
	global_load_dwordx4 v[160:163], v[196:197], off offset:1024
	global_load_dwordx4 v[164:167], v[196:197], off offset:2048
	global_load_dwordx4 v[168:171], v[196:197], off offset:3072
	global_load_dwordx4 v[172:175], v[198:199], off offset:0
	global_load_dwordx4 v[176:179], v[198:199], off offset:1024
	global_load_dwordx4 v[180:183], v[198:199], off offset:2048
	global_load_dwordx4 v[184:187], v[198:199], off offset:3072
	global_load_dwordx4 v[188:191], v[200:201], off offset:0
	s_and_saveexec_b64 s[92:93], s[90:91]
	global_load_dwordx4 v[192:195], v[200:201], off offset:1024
	s_mov_b64 exec, s[92:93]
	s_waitcnt vmcnt(0)
	global_store_dwordx4 v[16:17], v[140:143], off offset:0
	global_store_dwordx4 v[16:17], v[144:147], off offset:1024
	global_store_dwordx4 v[16:17], v[148:151], off offset:2048
	global_store_dwordx4 v[16:17], v[152:155], off offset:3072
	global_store_dwordx4 v[202:203], v[156:159], off offset:0
	global_store_dwordx4 v[202:203], v[160:163], off offset:1024
	global_store_dwordx4 v[202:203], v[164:167], off offset:2048
	global_store_dwordx4 v[202:203], v[168:171], off offset:3072
	global_store_dwordx4 v[204:205], v[172:175], off offset:0
	global_store_dwordx4 v[204:205], v[176:179], off offset:1024
	global_store_dwordx4 v[204:205], v[180:183], off offset:2048
	global_store_dwordx4 v[204:205], v[184:187], off offset:3072
	global_store_dwordx4 v[206:207], v[188:191], off offset:0
	s_and_saveexec_b64 s[92:93], s[90:91]
	global_store_dwordx4 v[206:207], v[192:195], off offset:1024
	s_mov_b64 exec, s[92:93]

.LBB0_697:
	s_or_b64 exec, exec, s[12:13]
	v_lshl_add_u32 v208, s2, 9, v231
	v_and_b32_e32 v209, 0xff, v231
	v_lshlrev_b32_e32 v209, 4, v209
	v_lshrrev_b32_e32 v210, 8, v208
	v_lshlrev_b32_e32 v211, 4, v208
	s_add_u32 s88, s16, 0x5429200
	s_addc_u32 s89, s17, 0
	s_mov_b32 s3, 0x88888889
	v_mov_b32_e32 v212, v210
	v_mul_hi_u32 v213, v212, s3
	v_lshrrev_b32_e32 v213, 4, v213
	v_mul_u32_u24_e32 v214, 30, v213
	v_sub_u32_e32 v215, v212, v214
	v_cmp_lt_u32_e64 s[90:91], 28, v215
	v_add_u32_e32 v214, 1, v212
	v_lshl_or_b32 v216, v214, 12, v209
	v_add_u32_e32 v214, 0x2000, v213
	v_lshl_or_b32 v217, v214, 12, v209
	s_and_saveexec_b64 s[92:93], s[90:91]
	global_load_dwordx4 v[140:143], v217, s[8:9]
	s_andn2_b64 exec, s[92:93], s[90:91]
	global_load_dwordx4 v[140:143], v216, s[14:15]
	s_mov_b64 exec, s[92:93]
	v_add_u32_e32 v212, 0x200, v210
	v_mul_hi_u32 v213, v212, s3
	v_lshrrev_b32_e32 v213, 4, v213
	v_mul_u32_u24_e32 v214, 30, v213
	v_sub_u32_e32 v215, v212, v214
	v_cmp_lt_u32_e64 s[90:91], 28, v215
	v_add_u32_e32 v214, 1, v212
	v_lshl_or_b32 v216, v214, 12, v209
	v_add_u32_e32 v214, 0x2000, v213
	v_lshl_or_b32 v217, v214, 12, v209
	s_and_saveexec_b64 s[92:93], s[90:91]
	global_load_dwordx4 v[144:147], v217, s[8:9]
	s_andn2_b64 exec, s[92:93], s[90:91]
	global_load_dwordx4 v[144:147], v216, s[14:15]
	s_mov_b64 exec, s[92:93]
	v_add_u32_e32 v212, 0x400, v210
	v_mul_hi_u32 v213, v212, s3
	v_lshrrev_b32_e32 v213, 4, v213
	v_mul_u32_u24_e32 v214, 30, v213
	v_sub_u32_e32 v215, v212, v214
	v_cmp_lt_u32_e64 s[90:91], 28, v215
	v_add_u32_e32 v214, 1, v212
	v_lshl_or_b32 v216, v214, 12, v209
	v_add_u32_e32 v214, 0x2000, v213
	v_lshl_or_b32 v217, v214, 12, v209
	s_and_saveexec_b64 s[92:93], s[90:91]
	global_load_dwordx4 v[148:151], v217, s[8:9]
	s_andn2_b64 exec, s[92:93], s[90:91]
	global_load_dwordx4 v[148:151], v216, s[14:15]
	s_mov_b64 exec, s[92:93]
	v_add_u32_e32 v212, 0x600, v210
	v_mul_hi_u32 v213, v212, s3
	v_lshrrev_b32_e32 v213, 4, v213
	v_mul_u32_u24_e32 v214, 30, v213
	v_sub_u32_e32 v215, v212, v214
	v_cmp_lt_u32_e64 s[90:91], 28, v215
	v_add_u32_e32 v214, 1, v212
	v_lshl_or_b32 v216, v214, 12, v209
	v_add_u32_e32 v214, 0x2000, v213
	v_lshl_or_b32 v217, v214, 12, v209
	s_and_saveexec_b64 s[92:93], s[90:91]
	global_load_dwordx4 v[152:155], v217, s[8:9]
	s_andn2_b64 exec, s[92:93], s[90:91]
	global_load_dwordx4 v[152:155], v216, s[14:15]
	s_mov_b64 exec, s[92:93]
	v_add_u32_e32 v212, 0x800, v210
	v_mul_hi_u32 v213, v212, s3
	v_lshrrev_b32_e32 v213, 4, v213
	v_mul_u32_u24_e32 v214, 30, v213
	v_sub_u32_e32 v215, v212, v214
	v_cmp_lt_u32_e64 s[90:91], 28, v215
	v_add_u32_e32 v214, 1, v212
	v_lshl_or_b32 v216, v214, 12, v209
	v_add_u32_e32 v214, 0x2000, v213
	v_lshl_or_b32 v217, v214, 12, v209
	s_and_saveexec_b64 s[92:93], s[90:91]
	global_load_dwordx4 v[156:159], v217, s[8:9]
	s_andn2_b64 exec, s[92:93], s[90:91]
	global_load_dwordx4 v[156:159], v216, s[14:15]
	s_mov_b64 exec, s[92:93]
	v_add_u32_e32 v212, 0xa00, v210
	v_mul_hi_u32 v213, v212, s3
	v_lshrrev_b32_e32 v213, 4, v213
	v_mul_u32_u24_e32 v214, 30, v213
	v_sub_u32_e32 v215, v212, v214
	v_cmp_lt_u32_e64 s[90:91], 28, v215
	v_add_u32_e32 v214, 1, v212
	v_lshl_or_b32 v216, v214, 12, v209
	v_add_u32_e32 v214, 0x2000, v213
	v_lshl_or_b32 v217, v214, 12, v209
	s_and_saveexec_b64 s[92:93], s[90:91]
	global_load_dwordx4 v[160:163], v217, s[8:9]
	s_andn2_b64 exec, s[92:93], s[90:91]
	global_load_dwordx4 v[160:163], v216, s[14:15]
	s_mov_b64 exec, s[92:93]
	v_add_u32_e32 v212, 0xc00, v210
	v_mul_hi_u32 v213, v212, s3
	v_lshrrev_b32_e32 v213, 4, v213
	v_mul_u32_u24_e32 v214, 30, v213
	v_sub_u32_e32 v215, v212, v214
	v_cmp_lt_u32_e64 s[90:91], 28, v215
	v_add_u32_e32 v214, 1, v212
	v_lshl_or_b32 v216, v214, 12, v209
	v_add_u32_e32 v214, 0x2000, v213
	v_lshl_or_b32 v217, v214, 12, v209
	s_and_saveexec_b64 s[92:93], s[90:91]
	global_load_dwordx4 v[164:167], v217, s[8:9]
	s_andn2_b64 exec, s[92:93], s[90:91]
	global_load_dwordx4 v[164:167], v216, s[14:15]
	s_mov_b64 exec, s[92:93]
	s_cmp_lt_u32 s2, 0x80
	s_cbranch_scc0 .Lp5_cvs_ld_done
	v_add_u32_e32 v212, 0xe00, v210
	v_mul_hi_u32 v213, v212, s3
	v_lshrrev_b32_e32 v213, 4, v213
	v_mul_u32_u24_e32 v214, 30, v213
	v_sub_u32_e32 v215, v212, v214
	v_cmp_lt_u32_e64 s[90:91], 28, v215
	v_add_u32_e32 v214, 1, v212
	v_lshl_or_b32 v216, v214, 12, v209
	v_add_u32_e32 v214, 0x2000, v213
	v_lshl_or_b32 v217, v214, 12, v209
	s_and_saveexec_b64 s[92:93], s[90:91]
	global_load_dwordx4 v[168:171], v217, s[8:9]
	s_andn2_b64 exec, s[92:93], s[90:91]
	global_load_dwordx4 v[168:171], v216, s[14:15]
	s_mov_b64 exec, s[92:93]
.Lp5_cvs_ld_done:
	s_waitcnt vmcnt(0)
	global_store_dwordx4 v211, v[140:143], s[88:89]
	s_add_u32 s88, s88, 0x200000
	s_addc_u32 s89, s89, 0
	global_store_dwordx4 v211, v[144:147], s[88:89]
	s_add_u32 s88, s88, 0x200000
	s_addc_u32 s89, s89, 0
	global_store_dwordx4 v211, v[148:151], s[88:89]
	s_add_u32 s88, s88, 0x200000
	s_addc_u32 s89, s89, 0
	global_store_dwordx4 v211, v[152:155], s[88:89]
	s_add_u32 s88, s88, 0x200000
	s_addc_u32 s89, s89, 0
	global_store_dwordx4 v211, v[156:159], s[88:89]
	s_add_u32 s88, s88, 0x200000
	s_addc_u32 s89, s89, 0
	global_store_dwordx4 v211, v[160:163], s[88:89]
	s_add_u32 s88, s88, 0x200000
	s_addc_u32 s89, s89, 0
	global_store_dwordx4 v211, v[164:167], s[88:89]
	s_add_u32 s88, s88, 0x200000
	s_addc_u32 s89, s89, 0
	s_cmp_lt_u32 s2, 0x80
	s_cbranch_scc0 .LBB0_704
	global_store_dwordx4 v211, v[168:171], s[88:89]
